# WABT/WOT (late-GEMM weight copies) stored sc1 nt in P0 so they do not take infinity-cache space from GEMM1 operands; on top of s_sleep 80 pacing
# baseline (speedup 1.0000x reference)
; #define LAS __attribute__((address_space(3)))
; __device__ __forceinline__ TItem t_decode(const Ptrs& P, int it, int lane) {
;     ...
;     if (r < 2 * I_A + I_O) {
;         const int nb = r % (D / 32), vbase = 32 * nb, col = (vbase + c4 & ~31) + pg8::perm32((vbase + c4) & 31);
;         if (r < I_A) { const int kb = r / (D / 32); t.N = D; t.ldk = 4096; t.src = P.w_a + (size_t)(64 * kb + r8) * D + col; t.dst = P.WABT + (size_t)vbase * 4096 + 64 * kb; return t; }
;         r -= I_A;
;         if (r < I_A) { const int kb = r / (D / 32); t.N = D; t.ldk = 4096; t.src = P.w_b + (size_t)(64 * kb + r8) * D + col; t.dst = P.WABT + (size_t)vbase * 4096 + HW + 64 * kb; return t; }
;         r -= I_A;
;         { const int kb = r / (D / 32); t.N = D; t.ldk = D; t.src = P.w_out + (size_t)(64 * kb + r8) * D + col; t.dst = P.WOT + (size_t)vbase * D + 64 * kb; return t; }
;     }
; __device__ __forceinline__ void p0_prologue(const Ptrs& P, LAS unsigned char* lds, int vcu, int G, int tid) {
;     ...
;             } else {
; #pragma unroll
;                 for (int j = 0; j < 4; ++j) { const int n = (lane >> 3) + 8 * j; const LAS float* sp = scr + (8 * c) * 33 + n;
;                     u32x4 o; o.x = pkg(sp[0 * 33], sp[1 * 33]); o.y = pkg(sp[2 * 33], sp[3 * 33]); o.z = pkg(sp[4 * 33], sp[5 * 33]); o.w = pkg(sp[6 * 33], sp[7 * 33]);
;                     *(u32x4*)(cur.dst + (size_t)n * cur.ldk + 8 * c) = o; }
;             }
.LBB0_37:
	s_sub_i32 s94, s50, s0
	s_cmpk_lt_i32 s94, 0x4000
	s_cbranch_scc1 .Lp0nt_37
	ds_read2_b32 v[6:7], v84 offset0:24 offset1:33
	ds_read2_b32 v[8:9], v84 offset0:57 offset1:66
	ds_read2_b32 v[10:11], v84 offset0:90 offset1:99
	ds_read2_b32 v[12:13], v84 offset0:123 offset1:132
	ds_read2_b32 v[14:15], v84 offset0:156 offset1:165
	ds_read2_b32 v[16:17], v84 offset0:189 offset1:198
	ds_read2_b32 v[18:19], v84 offset0:222 offset1:231
	ds_read2_b32 v[24:25], v84 offset0:8 offset1:16
	ds_read2_b32 v[26:27], v84 offset0:41 offset1:49
	ds_read2_b32 v[28:29], v84 offset0:74 offset1:82
	ds_read2_b32 v[30:31], v84 offset0:107 offset1:115
	ds_read2_b32 v[32:33], v84 offset0:140 offset1:148
	ds_read2_b32 v[78:79], v84 offset0:173 offset1:181
	ds_read2_b32 v[86:87], v84 offset0:206 offset1:214
	ds_read2_b32 v[88:89], v84 offset0:239 offset1:247
	v_lshlrev_b32_e32 v68, 1, v66
	v_lshl_add_u64 v[20:21], s[18:19], 0, v[68:69]
	v_lshlrev_b32_e32 v68, 1, v70
	s_waitcnt lgkmcnt(14)
	v_cvt_pk_bf16_f32 v2, v2, v7
	s_waitcnt lgkmcnt(8)
	v_cvt_pk_bf16_f32 v5, v17, v19
	v_lshl_add_u64 v[22:23], v[20:21], 0, v[68:69]
	v_lshlrev_b32_e32 v68, 1, v72
	v_cvt_pk_bf16_f32 v3, v9, v11
	v_cvt_pk_bf16_f32 v4, v13, v15
	global_store_dwordx4 v[22:23], v[2:5], off sc1
	v_lshl_add_u64 v[22:23], v[20:21], 0, v[68:69]
	v_lshlrev_b32_e32 v68, 1, v74
	s_waitcnt lgkmcnt(6)
	v_cvt_pk_bf16_f32 v2, v24, v26
	s_waitcnt lgkmcnt(0)
	v_cvt_pk_bf16_f32 v5, v86, v88
	v_cvt_pk_bf16_f32 v3, v28, v30
	v_cvt_pk_bf16_f32 v4, v32, v78
	global_store_dwordx4 v[22:23], v[2:5], off sc1
	v_lshl_add_u64 v[22:23], v[20:21], 0, v[68:69]
	ds_read_b32 v7, v84 offset:1020
	v_cvt_pk_bf16_f32 v2, v25, v27
	v_cvt_pk_bf16_f32 v5, v87, v89
	v_lshlrev_b32_e32 v68, 1, v76
	v_cvt_pk_bf16_f32 v3, v29, v31
	v_cvt_pk_bf16_f32 v4, v33, v79
	global_store_dwordx4 v[22:23], v[2:5], off sc1
	s_nop 1
	v_cvt_pk_bf16_f32 v2, v6, v8
	s_waitcnt lgkmcnt(0)
	v_cvt_pk_bf16_f32 v5, v18, v7
	v_lshl_add_u64 v[6:7], v[20:21], 0, v[68:69]
	v_cvt_pk_bf16_f32 v3, v10, v12
	v_cvt_pk_bf16_f32 v4, v14, v16
	global_store_dwordx4 v[6:7], v[2:5], off sc1

; #define LAS __attribute__((address_space(3)))
; __device__ __forceinline__ void p0_prologue(const Ptrs& P, LAS unsigned char* lds, int vcu, int G, int tid) {
;     ...
;             } else {
; #pragma unroll
;                 for (int j = 0; j < 4; ++j) { const int n = (lane >> 3) + 8 * j; const LAS float* sp = scr + (8 * c) * 33 + n;
;                     u32x4 o; o.x = pkg(sp[0 * 33], sp[1 * 33]); o.y = pkg(sp[2 * 33], sp[3 * 33]); o.z = pkg(sp[4 * 33], sp[5 * 33]); o.w = pkg(sp[6 * 33], sp[7 * 33]);
;                     *(u32x4*)(cur.dst + (size_t)n * cur.ldk + 8 * c) = o; }
;             }
.Lp0nt_37:
	ds_read2_b32 v[6:7], v84 offset0:24 offset1:33
	ds_read2_b32 v[8:9], v84 offset0:57 offset1:66
	ds_read2_b32 v[10:11], v84 offset0:90 offset1:99
	ds_read2_b32 v[12:13], v84 offset0:123 offset1:132
	ds_read2_b32 v[14:15], v84 offset0:156 offset1:165
	ds_read2_b32 v[16:17], v84 offset0:189 offset1:198
	ds_read2_b32 v[18:19], v84 offset0:222 offset1:231
	ds_read2_b32 v[24:25], v84 offset0:8 offset1:16
	ds_read2_b32 v[26:27], v84 offset0:41 offset1:49
	ds_read2_b32 v[28:29], v84 offset0:74 offset1:82
	ds_read2_b32 v[30:31], v84 offset0:107 offset1:115
	ds_read2_b32 v[32:33], v84 offset0:140 offset1:148
	ds_read2_b32 v[78:79], v84 offset0:173 offset1:181
	ds_read2_b32 v[86:87], v84 offset0:206 offset1:214
	ds_read2_b32 v[88:89], v84 offset0:239 offset1:247
	v_lshlrev_b32_e32 v68, 1, v66
	v_lshl_add_u64 v[20:21], s[18:19], 0, v[68:69]
	v_lshlrev_b32_e32 v68, 1, v70
	s_waitcnt lgkmcnt(14)
	v_cvt_pk_bf16_f32 v2, v2, v7
	s_waitcnt lgkmcnt(8)
	v_cvt_pk_bf16_f32 v5, v17, v19
	v_lshl_add_u64 v[22:23], v[20:21], 0, v[68:69]
	v_lshlrev_b32_e32 v68, 1, v72
	v_cvt_pk_bf16_f32 v3, v9, v11
	v_cvt_pk_bf16_f32 v4, v13, v15
	global_store_dwordx4 v[22:23], v[2:5], off sc1 nt
	v_lshl_add_u64 v[22:23], v[20:21], 0, v[68:69]
	v_lshlrev_b32_e32 v68, 1, v74
	s_waitcnt lgkmcnt(6)
	v_cvt_pk_bf16_f32 v2, v24, v26
	s_waitcnt lgkmcnt(0)
	v_cvt_pk_bf16_f32 v5, v86, v88
	v_cvt_pk_bf16_f32 v3, v28, v30
	v_cvt_pk_bf16_f32 v4, v32, v78
	global_store_dwordx4 v[22:23], v[2:5], off sc1 nt
	v_lshl_add_u64 v[22:23], v[20:21], 0, v[68:69]
	ds_read_b32 v7, v84 offset:1020
	v_cvt_pk_bf16_f32 v2, v25, v27
	v_cvt_pk_bf16_f32 v5, v87, v89
	v_lshlrev_b32_e32 v68, 1, v76
	v_cvt_pk_bf16_f32 v3, v29, v31
	v_cvt_pk_bf16_f32 v4, v33, v79
	global_store_dwordx4 v[22:23], v[2:5], off sc1 nt
	s_nop 1
	v_cvt_pk_bf16_f32 v2, v6, v8
	s_waitcnt lgkmcnt(0)
	v_cvt_pk_bf16_f32 v5, v18, v7
	v_lshl_add_u64 v[6:7], v[20:21], 0, v[68:69]
	v_cvt_pk_bf16_f32 v3, v10, v12
	v_cvt_pk_bf16_f32 v4, v14, v16
	global_store_dwordx4 v[6:7], v[2:5], off sc1 nt
	s_branch .LBB0_38
